# s5_carry chain: loads of the chunk states prefetched 4 steps ahead (unrolled x4, counted vmcnt) so each step no longer waits for the previous step's store to complete; on top of v5
# speedup vs baseline: 1.0049x; 1.0026x over previous
.LBB0_485:
	s_and_b64 s[24:25], s[0:1], exec
	s_cselect_b32 s24, 0, s40
	s_add_i32 s24, s24, s36
	s_lshl_b32 s24, s24, 5
	s_or_b32 s24, s24, s38
	s_ashr_i32 s25, s24, 31
	s_lshl_b64 s[24:25], s[24:25], 10
	v_lshl_or_b32 v10, v0, 3, s24
	v_mov_b32_e32 v11, s25
	v_lshl_add_u64 v[26:27], s[10:11], 0, v[10:11]
	v_lshl_add_u64 v[24:25], s[22:23], 0, v[10:11]
	s_and_b64 s[24:25], s[0:1], exec
	s_cselect_b32 s37, 0, -1
	s_lshl_b32 s36, s37, 16
	s_or_b32 s36, s36, 0x8000
	global_load_dwordx2 v[16:17], v[24:25], off
	v_lshl_add_u64 v[24:25], v[24:25], 0, s[36:37]
	global_load_dwordx2 v[18:19], v[24:25], off
	v_lshl_add_u64 v[24:25], v[24:25], 0, s[36:37]
	global_load_dwordx2 v[20:21], v[24:25], off
	v_lshl_add_u64 v[24:25], v[24:25], 0, s[36:37]
	global_load_dwordx2 v[22:23], v[24:25], off
	v_lshl_add_u64 v[24:25], v[24:25], 0, s[36:37]
	s_cmp_eq_u32 s40, 3
	s_cbranch_scc1 .Lcarry_short
	global_store_dwordx2 v[26:27], v[4:5], off
	v_lshl_add_u64 v[26:27], v[26:27], 0, s[36:37]
	v_pk_mul_f32 v[12:13], v[8:9], v[4:5] op_sel:[0,1]
	v_pk_fma_f32 v[14:15], v[6:7], v[4:5], v[12:13] neg_lo:[0,0,1] neg_hi:[0,0,1]
	v_pk_fma_f32 v[4:5], v[6:7], v[4:5], v[12:13] op_sel_hi:[1,0,1]
	v_mov_b32_e32 v15, v5
	s_waitcnt vmcnt(4)
	v_pk_add_f32 v[4:5], v[14:15], v[16:17]
	global_load_dwordx2 v[16:17], v[24:25], off
	v_lshl_add_u64 v[24:25], v[24:25], 0, s[36:37]
	global_store_dwordx2 v[26:27], v[4:5], off
	v_lshl_add_u64 v[26:27], v[26:27], 0, s[36:37]
	v_pk_mul_f32 v[12:13], v[8:9], v[4:5] op_sel:[0,1]
	v_pk_fma_f32 v[14:15], v[6:7], v[4:5], v[12:13] neg_lo:[0,0,1] neg_hi:[0,0,1]
	v_pk_fma_f32 v[4:5], v[6:7], v[4:5], v[12:13] op_sel_hi:[1,0,1]
	v_mov_b32_e32 v15, v5
	s_waitcnt vmcnt(5)
	v_pk_add_f32 v[4:5], v[14:15], v[18:19]
	global_load_dwordx2 v[18:19], v[24:25], off
	v_lshl_add_u64 v[24:25], v[24:25], 0, s[36:37]
	global_store_dwordx2 v[26:27], v[4:5], off
	v_lshl_add_u64 v[26:27], v[26:27], 0, s[36:37]
	v_pk_mul_f32 v[12:13], v[8:9], v[4:5] op_sel:[0,1]
	v_pk_fma_f32 v[14:15], v[6:7], v[4:5], v[12:13] neg_lo:[0,0,1] neg_hi:[0,0,1]
	v_pk_fma_f32 v[4:5], v[6:7], v[4:5], v[12:13] op_sel_hi:[1,0,1]
	v_mov_b32_e32 v15, v5
	s_waitcnt vmcnt(6)
	v_pk_add_f32 v[4:5], v[14:15], v[20:21]
	global_load_dwordx2 v[20:21], v[24:25], off
	v_lshl_add_u64 v[24:25], v[24:25], 0, s[36:37]
	global_store_dwordx2 v[26:27], v[4:5], off
	v_lshl_add_u64 v[26:27], v[26:27], 0, s[36:37]
	v_pk_mul_f32 v[12:13], v[8:9], v[4:5] op_sel:[0,1]
	v_pk_fma_f32 v[14:15], v[6:7], v[4:5], v[12:13] neg_lo:[0,0,1] neg_hi:[0,0,1]
	v_pk_fma_f32 v[4:5], v[6:7], v[4:5], v[12:13] op_sel_hi:[1,0,1]
	v_mov_b32_e32 v15, v5
	s_waitcnt vmcnt(7)
	v_pk_add_f32 v[4:5], v[14:15], v[22:23]
	global_load_dwordx2 v[22:23], v[24:25], off
	v_lshl_add_u64 v[24:25], v[24:25], 0, s[36:37]
	s_mov_b32 s40, 6
.Lcarry_mid:
	global_store_dwordx2 v[26:27], v[4:5], off
	v_lshl_add_u64 v[26:27], v[26:27], 0, s[36:37]
	v_pk_mul_f32 v[12:13], v[8:9], v[4:5] op_sel:[0,1]
	v_pk_fma_f32 v[14:15], v[6:7], v[4:5], v[12:13] neg_lo:[0,0,1] neg_hi:[0,0,1]
	v_pk_fma_f32 v[4:5], v[6:7], v[4:5], v[12:13] op_sel_hi:[1,0,1]
	v_mov_b32_e32 v15, v5
	s_waitcnt vmcnt(7)
	v_pk_add_f32 v[4:5], v[14:15], v[16:17]
	global_load_dwordx2 v[16:17], v[24:25], off
	v_lshl_add_u64 v[24:25], v[24:25], 0, s[36:37]
	global_store_dwordx2 v[26:27], v[4:5], off
	v_lshl_add_u64 v[26:27], v[26:27], 0, s[36:37]
	v_pk_mul_f32 v[12:13], v[8:9], v[4:5] op_sel:[0,1]
	v_pk_fma_f32 v[14:15], v[6:7], v[4:5], v[12:13] neg_lo:[0,0,1] neg_hi:[0,0,1]
	v_pk_fma_f32 v[4:5], v[6:7], v[4:5], v[12:13] op_sel_hi:[1,0,1]
	v_mov_b32_e32 v15, v5
	s_waitcnt vmcnt(7)
	v_pk_add_f32 v[4:5], v[14:15], v[18:19]
	global_load_dwordx2 v[18:19], v[24:25], off
	v_lshl_add_u64 v[24:25], v[24:25], 0, s[36:37]
	global_store_dwordx2 v[26:27], v[4:5], off
	v_lshl_add_u64 v[26:27], v[26:27], 0, s[36:37]
	v_pk_mul_f32 v[12:13], v[8:9], v[4:5] op_sel:[0,1]
	v_pk_fma_f32 v[14:15], v[6:7], v[4:5], v[12:13] neg_lo:[0,0,1] neg_hi:[0,0,1]
	v_pk_fma_f32 v[4:5], v[6:7], v[4:5], v[12:13] op_sel_hi:[1,0,1]
	v_mov_b32_e32 v15, v5
	s_waitcnt vmcnt(7)
	v_pk_add_f32 v[4:5], v[14:15], v[20:21]
	global_load_dwordx2 v[20:21], v[24:25], off
	v_lshl_add_u64 v[24:25], v[24:25], 0, s[36:37]
	global_store_dwordx2 v[26:27], v[4:5], off
	v_lshl_add_u64 v[26:27], v[26:27], 0, s[36:37]
	v_pk_mul_f32 v[12:13], v[8:9], v[4:5] op_sel:[0,1]
	v_pk_fma_f32 v[14:15], v[6:7], v[4:5], v[12:13] neg_lo:[0,0,1] neg_hi:[0,0,1]
	v_pk_fma_f32 v[4:5], v[6:7], v[4:5], v[12:13] op_sel_hi:[1,0,1]
	v_mov_b32_e32 v15, v5
	s_waitcnt vmcnt(7)
	v_pk_add_f32 v[4:5], v[14:15], v[22:23]
	global_load_dwordx2 v[22:23], v[24:25], off
	v_lshl_add_u64 v[24:25], v[24:25], 0, s[36:37]
	s_sub_i32 s40, s40, 1
	s_cmp_lg_u32 s40, 0
	s_cbranch_scc1 .Lcarry_mid
	global_store_dwordx2 v[26:27], v[4:5], off
	v_lshl_add_u64 v[26:27], v[26:27], 0, s[36:37]
	v_pk_mul_f32 v[12:13], v[8:9], v[4:5] op_sel:[0,1]
	v_pk_fma_f32 v[14:15], v[6:7], v[4:5], v[12:13] neg_lo:[0,0,1] neg_hi:[0,0,1]
	v_pk_fma_f32 v[4:5], v[6:7], v[4:5], v[12:13] op_sel_hi:[1,0,1]
	v_mov_b32_e32 v15, v5
	s_waitcnt vmcnt(7)
	v_pk_add_f32 v[4:5], v[14:15], v[16:17]
	global_store_dwordx2 v[26:27], v[4:5], off
	v_lshl_add_u64 v[26:27], v[26:27], 0, s[36:37]
	v_pk_mul_f32 v[12:13], v[8:9], v[4:5] op_sel:[0,1]
	v_pk_fma_f32 v[14:15], v[6:7], v[4:5], v[12:13] neg_lo:[0,0,1] neg_hi:[0,0,1]
	v_pk_fma_f32 v[4:5], v[6:7], v[4:5], v[12:13] op_sel_hi:[1,0,1]
	v_mov_b32_e32 v15, v5
	s_waitcnt vmcnt(6)
	v_pk_add_f32 v[4:5], v[14:15], v[18:19]
	global_store_dwordx2 v[26:27], v[4:5], off
	v_lshl_add_u64 v[26:27], v[26:27], 0, s[36:37]
	v_pk_mul_f32 v[12:13], v[8:9], v[4:5] op_sel:[0,1]
	v_pk_fma_f32 v[14:15], v[6:7], v[4:5], v[12:13] neg_lo:[0,0,1] neg_hi:[0,0,1]
	v_pk_fma_f32 v[4:5], v[6:7], v[4:5], v[12:13] op_sel_hi:[1,0,1]
	v_mov_b32_e32 v15, v5
	s_waitcnt vmcnt(5)
	v_pk_add_f32 v[4:5], v[14:15], v[20:21]
	global_store_dwordx2 v[26:27], v[4:5], off
	v_lshl_add_u64 v[26:27], v[26:27], 0, s[36:37]
	v_pk_mul_f32 v[12:13], v[8:9], v[4:5] op_sel:[0,1]
	v_pk_fma_f32 v[14:15], v[6:7], v[4:5], v[12:13] neg_lo:[0,0,1] neg_hi:[0,0,1]
	v_pk_fma_f32 v[4:5], v[6:7], v[4:5], v[12:13] op_sel_hi:[1,0,1]
	v_mov_b32_e32 v15, v5
	s_waitcnt vmcnt(4)
	v_pk_add_f32 v[4:5], v[14:15], v[22:23]
	s_branch .Lcarry_done
.Lcarry_short:
	global_store_dwordx2 v[26:27], v[4:5], off
	v_lshl_add_u64 v[26:27], v[26:27], 0, s[36:37]
	v_pk_mul_f32 v[12:13], v[8:9], v[4:5] op_sel:[0,1]
	v_pk_fma_f32 v[14:15], v[6:7], v[4:5], v[12:13] neg_lo:[0,0,1] neg_hi:[0,0,1]
	v_pk_fma_f32 v[4:5], v[6:7], v[4:5], v[12:13] op_sel_hi:[1,0,1]
	v_mov_b32_e32 v15, v5
	s_waitcnt vmcnt(4)
	v_pk_add_f32 v[4:5], v[14:15], v[16:17]
	global_store_dwordx2 v[26:27], v[4:5], off
	v_lshl_add_u64 v[26:27], v[26:27], 0, s[36:37]
	v_pk_mul_f32 v[12:13], v[8:9], v[4:5] op_sel:[0,1]
	v_pk_fma_f32 v[14:15], v[6:7], v[4:5], v[12:13] neg_lo:[0,0,1] neg_hi:[0,0,1]
	v_pk_fma_f32 v[4:5], v[6:7], v[4:5], v[12:13] op_sel_hi:[1,0,1]
	v_mov_b32_e32 v15, v5
	s_waitcnt vmcnt(4)
	v_pk_add_f32 v[4:5], v[14:15], v[18:19]
	global_store_dwordx2 v[26:27], v[4:5], off
	v_lshl_add_u64 v[26:27], v[26:27], 0, s[36:37]
	v_pk_mul_f32 v[12:13], v[8:9], v[4:5] op_sel:[0,1]
	v_pk_fma_f32 v[14:15], v[6:7], v[4:5], v[12:13] neg_lo:[0,0,1] neg_hi:[0,0,1]
	v_pk_fma_f32 v[4:5], v[6:7], v[4:5], v[12:13] op_sel_hi:[1,0,1]
	v_mov_b32_e32 v15, v5
	s_waitcnt vmcnt(4)
	v_pk_add_f32 v[4:5], v[14:15], v[20:21]
	global_store_dwordx2 v[26:27], v[4:5], off
	v_lshl_add_u64 v[26:27], v[26:27], 0, s[36:37]
	v_pk_mul_f32 v[12:13], v[8:9], v[4:5] op_sel:[0,1]
	v_pk_fma_f32 v[14:15], v[6:7], v[4:5], v[12:13] neg_lo:[0,0,1] neg_hi:[0,0,1]
	v_pk_fma_f32 v[4:5], v[6:7], v[4:5], v[12:13] op_sel_hi:[1,0,1]
	v_mov_b32_e32 v15, v5
	s_waitcnt vmcnt(4)
	v_pk_add_f32 v[4:5], v[14:15], v[22:23]
.Lcarry_done:
	s_and_b64 vcc, exec, s[20:21]
	s_cbranch_vccz .LBB0_480
	s_or_b32 s20, s35, s39
	s_ashr_i32 s21, s20, 31
	s_lshl_b64 s[20:21], s[20:21], 14
	v_readlane_b32 s24, v252, 37
	s_add_u32 s20, s24, s20
	v_readlane_b32 s24, v252, 38
	s_addc_u32 s21, s24, s21
	v_mov_b32_e32 v3, v193
	v_lshl_add_u64 v[6:7], s[20:21], 0, v[2:3]
	global_store_dword v2, v4, s[20:21]
	v_add_co_u32_e32 v2, vcc, 0x2000, v6
	s_nop 1
	v_addc_co_u32_e32 v3, vcc, 0, v7, vcc
	global_store_dword v[2:3], v5, off
	s_branch .LBB0_480
